# outproj gemm_big k-loop ported to the 3-stage LDS ring as well (all three gemm_big sites)
# speedup vs baseline: 1.0737x; 1.0051x over previous
; DI int otid() { int t; asm volatile("v_mov_b32 %0, %1" : "=v"(t) : "v"((int)threadIdx.x)); __builtin_assume(t >= 0 && t < 256); return t; }
; #define BLOADG(kt) do { \
;     _Pragma("unroll") for (int i = 0; i < 2; ++i) ra[i] = *(const u32x4*)(ap + (size_t)(64 * i) * lda + (kt) * 32); \
;     _Pragma("unroll") for (int i = 0; i < 4; ++i) rb[i] = *(const u32x4*)(bp + (size_t)((i & 1) * s1 + (i >> 1) * s2) * ldb + (kt) * 32); } while (0)
; #define BSTOREG(st) do { \
;     _Pragma("unroll") for (int i = 0; i < 2; ++i) *(u32x4*)(sA + (st) * BGA + so + 64 * i * 32) = ra[i]; \
;     _Pragma("unroll") for (int i = 0; i < 4; ++i) *(u32x4*)(sB + (st) * BGB + so + 64 * i * 32) = rb[i]; } while (0)
;     ...
;   const int tid = otid(), lane = tid & 63, wid = tid >> 6;
;   const int wm = wid >> 1, wn = wid & 1, fr = lane & 15, fq = lane >> 4;
;   const int nk = K >> 5;
;   const bf16_t* ap = A + (size_t)(tid >> 2) * lda + (tid & 3) * 8;
;   const bf16_t* bp = Bt + (size_t)(brow >= 0 ? brow : (tid >> 2)) * ldb + (tid & 3) * 8;
;   const int so = (tid >> 2) * 32 + (((tid & 3) ^ (((tid >> 5) & 1) << 1)) * 8);
;   const int fo = fr * 32 + ((fq ^ (((fr >> 3) & 1) << 1)) * 8);
;   u32x4 ra[2], rb[4];
;     ...
;   __syncthreads();
;   BLOADG(0); BSTOREG(0);
;   if (nk > 1) BLOADG(1);
;   __syncthreads();
; DI void outproj_tile(const Params& p, int l, int tile, char* smem) {
;   const int mt = tile & 255, nt = tile >> 8;
;   f32x4 acc[4][8]; zero_acc8(acc);
;   gemm_big(acc, P_PROJ + (size_t)mt * 128 * PW + C_MERGED, PW, P_WOT + ((size_t)l * 1024 + nt * 256) * 1024, 1024, 1024, smem);
.LBB0_237:
	s_and_b32 s22, s11, 0x300
	s_add_i32 s22, s12, s22
	s_and_b32 s22, s22, 0xffffff00
	s_ashr_i32 s23, s22, 31
	s_add_u32 s22, s6, s22
	s_addc_u32 s23, 0, s23
	s_and_b32 s24, s12, 0xc0
	v_readlane_b32 s27, v253, 55
	s_or_b32 s24, s27, s24
	s_and_b32 s25, s7, 7
	s_add_i32 s30, s24, s25
	s_lshl_b32 s25, s13, 1
	s_and_b32 s26, s13, 7
	s_and_b32 s24, s25, 0xc0
	s_or_b32 s26, s26, s27
	s_or_b32 s24, s26, s24
	s_lshl_b32 s26, s13, 5
	s_and_b32 s26, s26, 0x300
	s_lshl_b64 s[22:23], s[22:23], 11
	s_add_i32 s25, s26, s25
	s_mul_i32 s26, s24, 0x130000
	s_add_u32 s26, s58, s26
	s_addc_u32 s27, s59, 0
	s_and_b32 s25, s25, 0xffffff00
	s_ashr_i32 s29, s25, 31
	s_add_u32 s28, s6, s25
	s_addc_u32 s29, 0, s29
	v_mov_b32 v42, v188
	s_lshl_b64 s[28:29], s[28:29], 11
	v_lshrrev_b32_e32 v43, 2, v42
	v_readlane_b32 s34, v253, 20
	v_mul_u32_u24_e32 v0, 0x1300, v43
	s_add_u32 s28, s34, s28
	v_readlane_b32 s34, v253, 21
	v_lshlrev_b64 v[26:27], 1, v[0:1]
	v_and_b32_e32 v44, 3, v42
	s_addc_u32 s29, s34, s29
	v_lshl_add_u64 v[2:3], s[26:27], 0, v[26:27]
	v_lshlrev_b32_e32 v0, 4, v44
	v_lshlrev_b32_e32 v30, 11, v43
	v_mov_b32_e32 v31, v1
	v_lshl_add_u64 v[28:29], v[2:3], 0, v[0:1]
	v_lshl_add_u64 v[2:3], s[28:29], 0, v[30:31]
	v_lshl_add_u64 v[32:33], v[2:3], 0, v[0:1]
	v_add_co_u32_e32 v2, vcc, s16, v28
	s_nop 1
	v_addc_co_u32_e32 v3, vcc, 0, v29, vcc
	v_add_co_u32_e32 v34, vcc, s18, v28
	s_barrier
	s_nop 0
	v_addc_co_u32_e32 v35, vcc, 0, v29, vcc
	v_add_co_u32_e32 v36, vcc, s77, v32
	s_nop 1
	v_addc_co_u32_e32 v37, vcc, 0, v33, vcc
	v_add_co_u32_e32 v38, vcc, s92, v32
	v_lshrrev_b32_e32 v195, 6, v188
	v_lshlrev_b32_e32 v195, 10, v195
	v_lshrrev_b32_e32 v196, 4, v188
	v_and_b32_e32 v219, 3, v188
	v_and_b32_e32 v196, 2, v196
	v_xor_b32_e32 v191, v196, v219
	v_readfirstlane_b32 s100, v195
	s_sub_u32 s101, s18, s16
	s_add_u32 s26, s26, s16
	s_addc_u32 s27, s27, 0
	s_add_u32 s26, s26, 0x400
	s_addc_u32 s27, s27, 0
	v_lshrrev_b32_e32 v218, 2, v188
	v_mul_u32_u24_e32 v218, 0x2600, v218
	v_lshl_add_u32 v218, v191, 4, v218
	v_add_u32_e32 v219, s101, v218
	v_lshrrev_b32_e32 v220, 2, v188
	v_lshlrev_b32_e32 v220, 11, v220
	v_lshl_or_b32 v220, v191, 4, v220
	v_add_u32_e32 v221, 0x20000, v220
	v_add_u32_e32 v190, 0x40000, v220
	v_add_u32_e32 v191, 0x60000, v220
	s_mov_b32 m0, s100
	s_nop 0
	global_load_lds_dwordx4 v218, s[26:27]
	s_add_u32 m0, m0, 0x1fc0
	s_nop 0
	global_load_lds_dwordx4 v218, s[26:27] offset:64
	s_sub_u32 m0, m0, 0xfc0
	s_nop 0
	global_load_lds_dwordx4 v219, s[26:27]
	s_add_u32 m0, m0, 0x1fc0
	s_nop 0
	global_load_lds_dwordx4 v219, s[26:27] offset:64
	s_add_u32 m0, m0, 0x1040
	s_nop 0
	global_load_lds_dwordx4 v220, s[28:29]
	s_add_u32 m0, m0, 0x3fc0
	s_nop 0
	global_load_lds_dwordx4 v220, s[28:29] offset:64
	s_sub_u32 m0, m0, 0x2fc0
	s_nop 0
	global_load_lds_dwordx4 v221, s[28:29]
	s_add_u32 m0, m0, 0x3fc0
	s_nop 0
	global_load_lds_dwordx4 v221, s[28:29] offset:64
	s_sub_u32 m0, m0, 0x2fc0
	s_nop 0
	global_load_lds_dwordx4 v190, s[28:29]
	s_add_u32 m0, m0, 0x3fc0
	s_nop 0
	global_load_lds_dwordx4 v190, s[28:29] offset:64
	s_sub_u32 m0, m0, 0x2fc0
	s_nop 0
	global_load_lds_dwordx4 v191, s[28:29]
	s_add_u32 m0, m0, 0x3fc0
	s_nop 0
	global_load_lds_dwordx4 v191, s[28:29] offset:64
	s_add_u32 s26, s26, 0x80
	s_addc_u32 s27, s27, 0
	s_add_u32 s28, s28, 0x80
	s_addc_u32 s29, s29, 0
	s_sub_u32 m0, m0, 0x3fc0
	s_nop 0
	s_nop 0
	v_addc_co_u32_e32 v39, vcc, 0, v33, vcc
	v_add_co_u32_e32 v40, vcc, s81, v32
	v_addc_co_u32_e32 v41, vcc, 0, v33, vcc
	v_lshl_add_u64 v[28:29], v[28:29], 0, s[28:29]
	v_lshrrev_b32_e32 v45, 4, v42
	v_bitop3_b32 v44, v45, v44, 2 bitop3:0x6c
	v_and_b32_e32 v48, 2, v43
	v_lshlrev_b32_e32 v43, 6, v43
	v_lshl_or_b32 v164, v44, 4, v43
	s_mul_i32 s30, s30, 0x130000
	v_lshlrev_b32_e32 v47, 6, v42
	v_and_b32_e32 v47, 0x3c0, v47
	v_bitop3_b32 v45, v45, v48, 3 bitop3:0x6c
	v_lshlrev_b32_e32 v46, 5, v42
	v_lshlrev_b32_e32 v42, 7, v42
	v_lshl_or_b32 v43, v45, 4, v47
	v_and_or_b32 v163, v46, s85, v43
	v_and_or_b32 v162, v42, s35, v43
	v_lshl_add_u64 v[2:3], v[30:31], 0, s[22:23]
	v_or_b32_e32 v2, v2, v0
	v_or_b32_e32 v0, s30, v0
	v_lshl_add_u64 v[158:159], s[58:59], 0, v[2:3]
	v_lshl_add_u64 v[2:3], v[0:1], 0, v[26:27]
	v_lshl_add_u64 v[160:161], s[58:59], 0, v[2:3]
	v_mov_b32_e32 v2, 0
	s_mov_b64 s[22:23], 0
	v_mov_b32_e32 v3, v2
	v_mov_b32_e32 v4, v2
	v_mov_b32_e32 v5, v2
	v_mov_b32_e32 v6, v2
	v_mov_b32_e32 v7, v2
	v_mov_b32_e32 v8, v2
	v_mov_b32_e32 v9, v2
	v_mov_b32_e32 v10, v2
	v_mov_b32_e32 v11, v2
	v_mov_b32_e32 v12, v2
	v_mov_b32_e32 v13, v2
	v_mov_b32_e32 v14, v2
	v_mov_b32_e32 v15, v2
	v_mov_b32_e32 v16, v2
	v_mov_b32_e32 v17, v2
	v_mov_b32_e32 v50, v2
	v_mov_b32_e32 v51, v2
	v_mov_b32_e32 v52, v2
	v_mov_b32_e32 v53, v2
	v_mov_b32_e32 v54, v2
	v_mov_b32_e32 v55, v2
	v_mov_b32_e32 v56, v2
	v_mov_b32_e32 v57, v2
	v_mov_b32_e32 v62, v2
	v_mov_b32_e32 v63, v2
	v_mov_b32_e32 v64, v2
	v_mov_b32_e32 v65, v2
	v_mov_b32_e32 v66, v2
	v_mov_b32_e32 v67, v2
	v_mov_b32_e32 v68, v2
	v_mov_b32_e32 v69, v2
	v_mov_b32_e32 v18, v2
	v_mov_b32_e32 v19, v2
	v_mov_b32_e32 v20, v2
	v_mov_b32_e32 v21, v2
	v_mov_b32_e32 v22, v2
	v_mov_b32_e32 v23, v2
	v_mov_b32_e32 v24, v2
	v_mov_b32_e32 v25, v2
	v_mov_b32_e32 v26, v2
	v_mov_b32_e32 v27, v2
	v_mov_b32_e32 v28, v2
	v_mov_b32_e32 v29, v2
	v_mov_b32_e32 v30, v2
	v_mov_b32_e32 v31, v2
	v_mov_b32_e32 v32, v2
	v_mov_b32_e32 v33, v2
	v_mov_b32_e32 v74, v2
	v_mov_b32_e32 v75, v2
	v_mov_b32_e32 v76, v2
	v_mov_b32_e32 v77, v2
	v_mov_b32_e32 v78, v2
	v_mov_b32_e32 v79, v2
	v_mov_b32_e32 v80, v2
	v_mov_b32_e32 v81, v2
	v_mov_b32_e32 v86, v2
	v_mov_b32_e32 v87, v2
	v_mov_b32_e32 v88, v2
	v_mov_b32_e32 v89, v2
; #define BLOADG(kt) do { \
;     _Pragma("unroll") for (int i = 0; i < 2; ++i) ra[i] = *(const u32x4*)(ap + (size_t)(64 * i) * lda + (kt) * 32); \
;     _Pragma("unroll") for (int i = 0; i < 4; ++i) rb[i] = *(const u32x4*)(bp + (size_t)((i & 1) * s1 + (i >> 1) * s2) * ldb + (kt) * 32); } while (0)
; #define BSTOREG(st) do { \
;     _Pragma("unroll") for (int i = 0; i < 2; ++i) *(u32x4*)(sA + (st) * BGA + so + 64 * i * 32) = ra[i]; \
;     _Pragma("unroll") for (int i = 0; i < 4; ++i) *(u32x4*)(sB + (st) * BGB + so + 64 * i * 32) = rb[i]; } while (0)
;     ...
;   for (int kt = 0; kt < nk; ++kt) {
;     const int cur = kt & 1;
;     if (kt + 1 < nk) { BSTOREG(cur ^ 1); if (kt + 2 < nk) BLOADG(kt + 2); }
;     const bf16_t* cA = sA + cur * BGA + (wm * 64) * 32 + fo; const bf16_t* cB = sB + cur * BGB + (wn * 128) * 32 + fo;
;     bf16x8 af[4];
; #pragma unroll
;     for (int mi = 0; mi < 4; ++mi) af[mi] = *(const bf16x8*)(cA + mi * 16 * 32);
; #pragma unroll
;     for (int nh = 0; nh < 2; ++nh) {
;       bf16x8 bfr[4];
; #pragma unroll
;       for (int ni = 0; ni < 4; ++ni) bfr[ni] = *(const bf16x8*)(cB + (nh * 4 + ni) * 16 * 32);
; #pragma unroll
;       for (int mi = 0; mi < 4; ++mi)
; #pragma unroll
;         for (int ni = 0; ni < 4; ++ni) acc[mi][nh * 4 + ni] = __builtin_amdgcn_mfma_f32_16x16x32_bf16(bfr[ni], af[mi], acc[mi][nh * 4 + ni], 0, 0, 0);
;     }
; DI void zero_acc8(f32x4 (&acc)[4][8]) {
; #pragma unroll
;   for (int mi = 0; mi < 4; ++mi)
; #pragma unroll
;     for (int ni = 0; ni < 8; ++ni) acc[mi][ni] = f32x4{0.f, 0.f, 0.f, 0.f};
	v_mov_b32_e32 v98, v2
	v_mov_b32_e32 v99, v2
	v_mov_b32_e32 v100, v2
	v_mov_b32_e32 v101, v2
	v_mov_b32_e32 v34, v2
	v_mov_b32_e32 v35, v2
	v_mov_b32_e32 v36, v2
	v_mov_b32_e32 v37, v2
	v_mov_b32_e32 v38, v2
	v_mov_b32_e32 v39, v2
	v_mov_b32_e32 v40, v2
	v_mov_b32_e32 v41, v2
	v_mov_b32_e32 v42, v2
	v_mov_b32_e32 v43, v2
	v_mov_b32_e32 v44, v2
	v_mov_b32_e32 v45, v2
	v_mov_b32_e32 v46, v2
	v_mov_b32_e32 v47, v2
	v_mov_b32_e32 v48, v2
	v_mov_b32_e32 v49, v2
	v_mov_b32_e32 v122, v2
	v_mov_b32_e32 v123, v2
	v_mov_b32_e32 v124, v2
	v_mov_b32_e32 v125, v2
	v_mov_b32_e32 v126, v2
	v_mov_b32_e32 v127, v2
	v_mov_b32_e32 v128, v2
	v_mov_b32_e32 v129, v2
	v_mov_b32_e32 v130, v2
	v_mov_b32_e32 v131, v2
	v_mov_b32_e32 v132, v2
	v_mov_b32_e32 v133, v2
	v_mov_b32_e32 v134, v2
	v_mov_b32_e32 v135, v2
	v_mov_b32_e32 v136, v2
	v_mov_b32_e32 v137, v2
	v_mov_b32_e32 v58, v2
	v_mov_b32_e32 v59, v2
	v_mov_b32_e32 v60, v2
	v_mov_b32_e32 v61, v2
	v_mov_b32_e32 v70, v2
	v_mov_b32_e32 v71, v2
	v_mov_b32_e32 v72, v2
	v_mov_b32_e32 v73, v2
	v_mov_b32_e32 v82, v2
	v_mov_b32_e32 v83, v2
	v_mov_b32_e32 v84, v2
	v_mov_b32_e32 v85, v2
	v_mov_b32_e32 v102, v2
	v_mov_b32_e32 v103, v2
	v_mov_b32_e32 v104, v2
	v_mov_b32_e32 v105, v2
	v_mov_b32_e32 v138, v2
	v_mov_b32_e32 v139, v2
	v_mov_b32_e32 v140, v2
	v_mov_b32_e32 v141, v2
	v_mov_b32_e32 v142, v2
	v_mov_b32_e32 v143, v2
	v_mov_b32_e32 v144, v2
	v_mov_b32_e32 v145, v2
	v_mov_b32_e32 v146, v2
	v_mov_b32_e32 v147, v2
	v_mov_b32_e32 v148, v2
	v_mov_b32_e32 v149, v2
	v_mov_b32_e32 v150, v2
	v_mov_b32_e32 v151, v2
	v_mov_b32_e32 v152, v2
	v_mov_b32_e32 v153, v2
	v_add_u32_e32 v192, 0x8000, v163
	v_lshlrev_b32_e32 v193, 4, v188
	v_add_u32_e32 v194, 0x8000, v193
	s_waitcnt vmcnt(0)
	s_barrier
.LBB0_238:
	ds_read_b128 v[166:169], v163 offset:0
	ds_read_b128 v[170:173], v163 offset:1024
	ds_read_b128 v[174:177], v163 offset:2048
	ds_read_b128 v[178:181], v163 offset:3072
	ds_read_b128 v[182:185], v162 offset:16384
	ds_read_b128 v[206:209], v162 offset:17408
	ds_read_b128 v[210:213], v162 offset:18432
	ds_read_b128 v[214:217], v162 offset:19456
	s_waitcnt lgkmcnt(7)
	s_waitcnt lgkmcnt(3)
	v_mfma_f32_16x16x32_bf16 v[150:153], v[182:185], v[166:169], v[150:153]
	v_mfma_f32_16x16x32_bf16 v[134:137], v[182:185], v[170:173], v[134:137]
	v_mfma_f32_16x16x32_bf16 v[98:101], v[182:185], v[174:177], v[98:101]
	v_mfma_f32_16x16x32_bf16 v[66:69], v[182:185], v[178:181], v[66:69]
	ds_read_b128 v[182:185], v162 offset:20480
	s_add_u32 m0, m0, 0x9400
	s_nop 0
	global_load_lds_dwordx4 v218, s[26:27]
	global_load_dwordx4 v[118:121], v218, s[26:27] offset:64
	s_waitcnt lgkmcnt(3)
	v_mfma_f32_16x16x32_bf16 v[146:149], v[206:209], v[166:169], v[146:149]
	v_mfma_f32_16x16x32_bf16 v[130:133], v[206:209], v[170:173], v[130:133]
	v_mfma_f32_16x16x32_bf16 v[86:89], v[206:209], v[174:177], v[86:89]
	v_mfma_f32_16x16x32_bf16 v[62:65], v[206:209], v[178:181], v[62:65]
	ds_read_b128 v[206:209], v162 offset:21504
	s_add_u32 m0, m0, 0x1000
	s_nop 0
	global_load_lds_dwordx4 v219, s[26:27]
	global_load_dwordx4 v[114:117], v219, s[26:27] offset:64
	s_waitcnt lgkmcnt(3)
	v_mfma_f32_16x16x32_bf16 v[142:145], v[210:213], v[166:169], v[142:145]
	v_mfma_f32_16x16x32_bf16 v[126:129], v[210:213], v[170:173], v[126:129]
	v_mfma_f32_16x16x32_bf16 v[78:81], v[210:213], v[174:177], v[78:81]
	v_mfma_f32_16x16x32_bf16 v[54:57], v[210:213], v[178:181], v[54:57]
	ds_read_b128 v[210:213], v162 offset:22528
	s_sub_u32 m0, m0, 0x5400
	s_nop 0
	global_load_lds_dwordx4 v220, s[28:29]
	global_load_dwordx4 v[110:113], v220, s[28:29] offset:64
	s_waitcnt lgkmcnt(3)
	v_mfma_f32_16x16x32_bf16 v[138:141], v[214:217], v[166:169], v[138:141]
	v_mfma_f32_16x16x32_bf16 v[122:125], v[214:217], v[170:173], v[122:125]
	v_mfma_f32_16x16x32_bf16 v[74:77], v[214:217], v[174:177], v[74:77]
	v_mfma_f32_16x16x32_bf16 v[50:53], v[214:217], v[178:181], v[50:53]
	ds_read_b128 v[214:217], v162 offset:23552
	s_add_u32 m0, m0, 0x1000
	s_nop 0
	global_load_lds_dwordx4 v221, s[28:29]
	global_load_dwordx4 v[106:109], v221, s[28:29] offset:64
	s_waitcnt lgkmcnt(3)
	v_mfma_f32_16x16x32_bf16 v[102:105], v[182:185], v[166:169], v[102:105]
	v_mfma_f32_16x16x32_bf16 v[46:49], v[182:185], v[170:173], v[46:49]
	v_mfma_f32_16x16x32_bf16 v[30:33], v[182:185], v[174:177], v[30:33]
	v_mfma_f32_16x16x32_bf16 v[14:17], v[182:185], v[178:181], v[14:17]
	s_add_u32 m0, m0, 0x1000
	s_nop 0
	global_load_lds_dwordx4 v190, s[28:29]
	global_load_dwordx4 v[90:93], v190, s[28:29] offset:64
	s_waitcnt lgkmcnt(2)
	v_mfma_f32_16x16x32_bf16 v[82:85], v[206:209], v[166:169], v[82:85]
	v_mfma_f32_16x16x32_bf16 v[42:45], v[206:209], v[170:173], v[42:45]
	v_mfma_f32_16x16x32_bf16 v[26:29], v[206:209], v[174:177], v[26:29]
	v_mfma_f32_16x16x32_bf16 v[10:13], v[206:209], v[178:181], v[10:13]
	s_add_u32 m0, m0, 0x1000
	s_nop 0
	global_load_lds_dwordx4 v191, s[28:29]
	global_load_dwordx4 v[94:97], v191, s[28:29] offset:64
	s_add_u32 s26, s26, 0x80
	s_addc_u32 s27, s27, 0
	s_add_u32 s28, s28, 0x80
	s_addc_u32 s29, s29, 0
	s_waitcnt lgkmcnt(1)
	v_mfma_f32_16x16x32_bf16 v[70:73], v[210:213], v[166:169], v[70:73]
	v_mfma_f32_16x16x32_bf16 v[38:41], v[210:213], v[170:173], v[38:41]
	v_mfma_f32_16x16x32_bf16 v[22:25], v[210:213], v[174:177], v[22:25]
	v_mfma_f32_16x16x32_bf16 v[6:9], v[210:213], v[178:181], v[6:9]
	s_waitcnt lgkmcnt(0)
	s_barrier
; #define BLOADG(kt) do { \
;     _Pragma("unroll") for (int i = 0; i < 2; ++i) ra[i] = *(const u32x4*)(ap + (size_t)(64 * i) * lda + (kt) * 32); \
;     _Pragma("unroll") for (int i = 0; i < 4; ++i) rb[i] = *(const u32x4*)(bp + (size_t)((i & 1) * s1 + (i >> 1) * s2) * ldb + (kt) * 32); } while (0)
; #define BSTOREG(st) do { \
;     _Pragma("unroll") for (int i = 0; i < 2; ++i) *(u32x4*)(sA + (st) * BGA + so + 64 * i * 32) = ra[i]; \
;     _Pragma("unroll") for (int i = 0; i < 4; ++i) *(u32x4*)(sB + (st) * BGB + so + 64 * i * 32) = rb[i]; } while (0)
;     ...
;   for (int kt = 0; kt < nk; ++kt) {
;     const int cur = kt & 1;
;     if (kt + 1 < nk) { BSTOREG(cur ^ 1); if (kt + 2 < nk) BLOADG(kt + 2); }
;     const bf16_t* cA = sA + cur * BGA + (wm * 64) * 32 + fo; const bf16_t* cB = sB + cur * BGB + (wn * 128) * 32 + fo;
;     bf16x8 af[4];
; #pragma unroll
;     for (int mi = 0; mi < 4; ++mi) af[mi] = *(const bf16x8*)(cA + mi * 16 * 32);
; #pragma unroll
;     for (int nh = 0; nh < 2; ++nh) {
;       bf16x8 bfr[4];
; #pragma unroll
;       for (int ni = 0; ni < 4; ++ni) bfr[ni] = *(const bf16x8*)(cB + (nh * 4 + ni) * 16 * 32);
; #pragma unroll
;       for (int mi = 0; mi < 4; ++mi)
; #pragma unroll
;         for (int ni = 0; ni < 4; ++ni) acc[mi][nh * 4 + ni] = __builtin_amdgcn_mfma_f32_16x16x32_bf16(bfr[ni], af[mi], acc[mi][nh * 4 + ni], 0, 0, 0);
;     }
;     __syncthreads();
	v_mfma_f32_16x16x32_bf16 v[58:61], v[214:217], v[166:169], v[58:61]
	v_mfma_f32_16x16x32_bf16 v[34:37], v[214:217], v[170:173], v[34:37]
	v_mfma_f32_16x16x32_bf16 v[18:21], v[214:217], v[174:177], v[18:21]
	v_mfma_f32_16x16x32_bf16 v[2:5], v[214:217], v[178:181], v[2:5]
	ds_read_b128 v[166:169], v163 offset:8192
	ds_read_b128 v[170:173], v163 offset:9216
	ds_read_b128 v[174:177], v163 offset:10240
	ds_read_b128 v[178:181], v163 offset:11264
	ds_read_b128 v[182:185], v162 offset:32768
	ds_read_b128 v[206:209], v162 offset:33792
	ds_read_b128 v[210:213], v162 offset:34816
	ds_read_b128 v[214:217], v162 offset:35840
	s_waitcnt lgkmcnt(7)
	s_waitcnt lgkmcnt(3)
	v_mfma_f32_16x16x32_bf16 v[150:153], v[182:185], v[166:169], v[150:153]
	v_mfma_f32_16x16x32_bf16 v[134:137], v[182:185], v[170:173], v[134:137]
	v_mfma_f32_16x16x32_bf16 v[98:101], v[182:185], v[174:177], v[98:101]
	v_mfma_f32_16x16x32_bf16 v[66:69], v[182:185], v[178:181], v[66:69]
	ds_read_b128 v[182:185], v162 offset:36864
	s_waitcnt lgkmcnt(3)
	v_mfma_f32_16x16x32_bf16 v[146:149], v[206:209], v[166:169], v[146:149]
	v_mfma_f32_16x16x32_bf16 v[130:133], v[206:209], v[170:173], v[130:133]
	v_mfma_f32_16x16x32_bf16 v[86:89], v[206:209], v[174:177], v[86:89]
	v_mfma_f32_16x16x32_bf16 v[62:65], v[206:209], v[178:181], v[62:65]
	ds_read_b128 v[206:209], v162 offset:37888
	s_waitcnt lgkmcnt(3)
	v_mfma_f32_16x16x32_bf16 v[142:145], v[210:213], v[166:169], v[142:145]
	v_mfma_f32_16x16x32_bf16 v[126:129], v[210:213], v[170:173], v[126:129]
	v_mfma_f32_16x16x32_bf16 v[78:81], v[210:213], v[174:177], v[78:81]
	v_mfma_f32_16x16x32_bf16 v[54:57], v[210:213], v[178:181], v[54:57]
	ds_read_b128 v[210:213], v162 offset:38912
	s_waitcnt lgkmcnt(3)
	v_mfma_f32_16x16x32_bf16 v[138:141], v[214:217], v[166:169], v[138:141]
	v_mfma_f32_16x16x32_bf16 v[122:125], v[214:217], v[170:173], v[122:125]
	v_mfma_f32_16x16x32_bf16 v[74:77], v[214:217], v[174:177], v[74:77]
	v_mfma_f32_16x16x32_bf16 v[50:53], v[214:217], v[178:181], v[50:53]
	ds_read_b128 v[214:217], v162 offset:39936
	s_waitcnt lgkmcnt(3)
	v_mfma_f32_16x16x32_bf16 v[102:105], v[182:185], v[166:169], v[102:105]
	v_mfma_f32_16x16x32_bf16 v[46:49], v[182:185], v[170:173], v[46:49]
	v_mfma_f32_16x16x32_bf16 v[30:33], v[182:185], v[174:177], v[30:33]
	v_mfma_f32_16x16x32_bf16 v[14:17], v[182:185], v[178:181], v[14:17]
	s_waitcnt vmcnt(0)
	s_waitcnt lgkmcnt(2)
	v_mfma_f32_16x16x32_bf16 v[82:85], v[206:209], v[166:169], v[82:85]
	ds_write_b128 v193, v[118:121] offset:0
	v_mfma_f32_16x16x32_bf16 v[42:45], v[206:209], v[170:173], v[42:45]
	ds_write_b128 v193, v[114:117] offset:4096
	v_mfma_f32_16x16x32_bf16 v[26:29], v[206:209], v[174:177], v[26:29]
	ds_write_b128 v193, v[110:113] offset:16384
	v_mfma_f32_16x16x32_bf16 v[10:13], v[206:209], v[178:181], v[10:13]
	ds_write_b128 v193, v[106:109] offset:20480
	s_waitcnt lgkmcnt(5)
	v_mfma_f32_16x16x32_bf16 v[70:73], v[210:213], v[166:169], v[70:73]
	ds_write_b128 v193, v[90:93] offset:24576
	v_mfma_f32_16x16x32_bf16 v[38:41], v[210:213], v[170:173], v[38:41]
	ds_write_b128 v193, v[94:97] offset:28672
	v_mfma_f32_16x16x32_bf16 v[22:25], v[210:213], v[174:177], v[22:25]
	v_mfma_f32_16x16x32_bf16 v[6:9], v[210:213], v[178:181], v[6:9]
	s_waitcnt lgkmcnt(0)
	s_barrier
	v_mfma_f32_16x16x32_bf16 v[58:61], v[214:217], v[166:169], v[58:61]
	v_mfma_f32_16x16x32_bf16 v[34:37], v[214:217], v[170:173], v[34:37]
	v_mfma_f32_16x16x32_bf16 v[18:21], v[214:217], v[174:177], v[18:21]
	v_mfma_f32_16x16x32_bf16 v[2:5], v[214:217], v[178:181], v[2:5]
	ds_read_b128 v[166:169], v192 offset:33792
	ds_read_b128 v[170:173], v192 offset:34816
	ds_read_b128 v[174:177], v192 offset:35840
	ds_read_b128 v[178:181], v192 offset:36864
	ds_read_b128 v[182:185], v162 offset:49152
	ds_read_b128 v[206:209], v162 offset:50176
	ds_read_b128 v[210:213], v162 offset:51200
	ds_read_b128 v[214:217], v162 offset:52224
	s_waitcnt lgkmcnt(7)
	s_waitcnt lgkmcnt(3)
	v_mfma_f32_16x16x32_bf16 v[150:153], v[182:185], v[166:169], v[150:153]
	v_mfma_f32_16x16x32_bf16 v[134:137], v[182:185], v[170:173], v[134:137]
	v_mfma_f32_16x16x32_bf16 v[98:101], v[182:185], v[174:177], v[98:101]
	v_mfma_f32_16x16x32_bf16 v[66:69], v[182:185], v[178:181], v[66:69]
	ds_read_b128 v[182:185], v162 offset:53248
	s_sub_u32 m0, m0, 0xd000
	s_nop 0
	global_load_lds_dwordx4 v218, s[26:27]
	global_load_dwordx4 v[118:121], v218, s[26:27] offset:64
	s_waitcnt lgkmcnt(3)
	v_mfma_f32_16x16x32_bf16 v[146:149], v[206:209], v[166:169], v[146:149]
	v_mfma_f32_16x16x32_bf16 v[130:133], v[206:209], v[170:173], v[130:133]
	v_mfma_f32_16x16x32_bf16 v[86:89], v[206:209], v[174:177], v[86:89]
	v_mfma_f32_16x16x32_bf16 v[62:65], v[206:209], v[178:181], v[62:65]
	ds_read_b128 v[206:209], v162 offset:54272
	s_add_u32 m0, m0, 0x1000
	s_nop 0
	global_load_lds_dwordx4 v219, s[26:27]
	global_load_dwordx4 v[114:117], v219, s[26:27] offset:64
	s_waitcnt lgkmcnt(3)
	v_mfma_f32_16x16x32_bf16 v[142:145], v[210:213], v[166:169], v[142:145]
	v_mfma_f32_16x16x32_bf16 v[126:129], v[210:213], v[170:173], v[126:129]
	v_mfma_f32_16x16x32_bf16 v[78:81], v[210:213], v[174:177], v[78:81]
	v_mfma_f32_16x16x32_bf16 v[54:57], v[210:213], v[178:181], v[54:57]
	ds_read_b128 v[210:213], v162 offset:55296
	s_add_u32 m0, m0, 0x5000
	s_nop 0
	global_load_lds_dwordx4 v220, s[28:29]
	global_load_dwordx4 v[110:113], v220, s[28:29] offset:64
	s_waitcnt lgkmcnt(3)
	v_mfma_f32_16x16x32_bf16 v[138:141], v[214:217], v[166:169], v[138:141]
	v_mfma_f32_16x16x32_bf16 v[122:125], v[214:217], v[170:173], v[122:125]
	v_mfma_f32_16x16x32_bf16 v[74:77], v[214:217], v[174:177], v[74:77]
	v_mfma_f32_16x16x32_bf16 v[50:53], v[214:217], v[178:181], v[50:53]
	ds_read_b128 v[214:217], v162 offset:56320
	s_add_u32 m0, m0, 0x1000
	s_nop 0
	global_load_lds_dwordx4 v221, s[28:29]
	global_load_dwordx4 v[106:109], v221, s[28:29] offset:64
	s_waitcnt lgkmcnt(3)
; #define BLOADG(kt) do { \
;     _Pragma("unroll") for (int i = 0; i < 2; ++i) ra[i] = *(const u32x4*)(ap + (size_t)(64 * i) * lda + (kt) * 32); \
;     _Pragma("unroll") for (int i = 0; i < 4; ++i) rb[i] = *(const u32x4*)(bp + (size_t)((i & 1) * s1 + (i >> 1) * s2) * ldb + (kt) * 32); } while (0)
; #define BSTOREG(st) do { \
;     _Pragma("unroll") for (int i = 0; i < 2; ++i) *(u32x4*)(sA + (st) * BGA + so + 64 * i * 32) = ra[i]; \
;     _Pragma("unroll") for (int i = 0; i < 4; ++i) *(u32x4*)(sB + (st) * BGB + so + 64 * i * 32) = rb[i]; } while (0)
;     ...
;   for (int kt = 0; kt < nk; ++kt) {
;     const int cur = kt & 1;
;     if (kt + 1 < nk) { BSTOREG(cur ^ 1); if (kt + 2 < nk) BLOADG(kt + 2); }
;     const bf16_t* cA = sA + cur * BGA + (wm * 64) * 32 + fo; const bf16_t* cB = sB + cur * BGB + (wn * 128) * 32 + fo;
;     bf16x8 af[4];
; #pragma unroll
;     for (int mi = 0; mi < 4; ++mi) af[mi] = *(const bf16x8*)(cA + mi * 16 * 32);
; #pragma unroll
;     for (int nh = 0; nh < 2; ++nh) {
;       bf16x8 bfr[4];
; #pragma unroll
;       for (int ni = 0; ni < 4; ++ni) bfr[ni] = *(const bf16x8*)(cB + (nh * 4 + ni) * 16 * 32);
; #pragma unroll
;       for (int mi = 0; mi < 4; ++mi)
; #pragma unroll
;         for (int ni = 0; ni < 4; ++ni) acc[mi][nh * 4 + ni] = __builtin_amdgcn_mfma_f32_16x16x32_bf16(bfr[ni], af[mi], acc[mi][nh * 4 + ni], 0, 0, 0);
;     }
;     __syncthreads();
	v_mfma_f32_16x16x32_bf16 v[102:105], v[182:185], v[166:169], v[102:105]
	v_mfma_f32_16x16x32_bf16 v[46:49], v[182:185], v[170:173], v[46:49]
	v_mfma_f32_16x16x32_bf16 v[30:33], v[182:185], v[174:177], v[30:33]
	v_mfma_f32_16x16x32_bf16 v[14:17], v[182:185], v[178:181], v[14:17]
	s_add_u32 m0, m0, 0x1000
	s_nop 0
	global_load_lds_dwordx4 v190, s[28:29]
	global_load_dwordx4 v[90:93], v190, s[28:29] offset:64
	s_waitcnt lgkmcnt(2)
	v_mfma_f32_16x16x32_bf16 v[82:85], v[206:209], v[166:169], v[82:85]
	v_mfma_f32_16x16x32_bf16 v[42:45], v[206:209], v[170:173], v[42:45]
	v_mfma_f32_16x16x32_bf16 v[26:29], v[206:209], v[174:177], v[26:29]
	v_mfma_f32_16x16x32_bf16 v[10:13], v[206:209], v[178:181], v[10:13]
	s_add_u32 m0, m0, 0x1000
	s_nop 0
	global_load_lds_dwordx4 v191, s[28:29]
	global_load_dwordx4 v[94:97], v191, s[28:29] offset:64
	s_add_u32 s26, s26, 0x80
	s_addc_u32 s27, s27, 0
	s_add_u32 s28, s28, 0x80
	s_addc_u32 s29, s29, 0
	s_waitcnt lgkmcnt(1)
	v_mfma_f32_16x16x32_bf16 v[70:73], v[210:213], v[166:169], v[70:73]
	v_mfma_f32_16x16x32_bf16 v[38:41], v[210:213], v[170:173], v[38:41]
	v_mfma_f32_16x16x32_bf16 v[22:25], v[210:213], v[174:177], v[22:25]
	v_mfma_f32_16x16x32_bf16 v[6:9], v[210:213], v[178:181], v[6:9]
	s_waitcnt lgkmcnt(0)
	s_barrier
	v_mfma_f32_16x16x32_bf16 v[58:61], v[214:217], v[166:169], v[58:61]
	v_mfma_f32_16x16x32_bf16 v[34:37], v[214:217], v[170:173], v[34:37]
	v_mfma_f32_16x16x32_bf16 v[18:21], v[214:217], v[174:177], v[18:21]
	v_mfma_f32_16x16x32_bf16 v[2:5], v[214:217], v[178:181], v[2:5]
	ds_read_b128 v[166:169], v163 offset:0
	ds_read_b128 v[170:173], v163 offset:1024
	ds_read_b128 v[174:177], v163 offset:2048
	ds_read_b128 v[178:181], v163 offset:3072
	ds_read_b128 v[182:185], v162 offset:16384
	ds_read_b128 v[206:209], v162 offset:17408
	ds_read_b128 v[210:213], v162 offset:18432
	ds_read_b128 v[214:217], v162 offset:19456
	s_waitcnt lgkmcnt(7)
	s_waitcnt lgkmcnt(3)
	v_mfma_f32_16x16x32_bf16 v[150:153], v[182:185], v[166:169], v[150:153]
	v_mfma_f32_16x16x32_bf16 v[134:137], v[182:185], v[170:173], v[134:137]
	v_mfma_f32_16x16x32_bf16 v[98:101], v[182:185], v[174:177], v[98:101]
	v_mfma_f32_16x16x32_bf16 v[66:69], v[182:185], v[178:181], v[66:69]
	ds_read_b128 v[182:185], v162 offset:20480
	s_waitcnt lgkmcnt(3)
	v_mfma_f32_16x16x32_bf16 v[146:149], v[206:209], v[166:169], v[146:149]
	v_mfma_f32_16x16x32_bf16 v[130:133], v[206:209], v[170:173], v[130:133]
	v_mfma_f32_16x16x32_bf16 v[86:89], v[206:209], v[174:177], v[86:89]
	v_mfma_f32_16x16x32_bf16 v[62:65], v[206:209], v[178:181], v[62:65]
	ds_read_b128 v[206:209], v162 offset:21504
	s_waitcnt lgkmcnt(3)
	v_mfma_f32_16x16x32_bf16 v[142:145], v[210:213], v[166:169], v[142:145]
	v_mfma_f32_16x16x32_bf16 v[126:129], v[210:213], v[170:173], v[126:129]
	v_mfma_f32_16x16x32_bf16 v[78:81], v[210:213], v[174:177], v[78:81]
	v_mfma_f32_16x16x32_bf16 v[54:57], v[210:213], v[178:181], v[54:57]
	ds_read_b128 v[210:213], v162 offset:22528
	s_waitcnt lgkmcnt(3)
	v_mfma_f32_16x16x32_bf16 v[138:141], v[214:217], v[166:169], v[138:141]
	v_mfma_f32_16x16x32_bf16 v[122:125], v[214:217], v[170:173], v[122:125]
	v_mfma_f32_16x16x32_bf16 v[74:77], v[214:217], v[174:177], v[74:77]
	v_mfma_f32_16x16x32_bf16 v[50:53], v[214:217], v[178:181], v[50:53]
	ds_read_b128 v[214:217], v162 offset:23552
	s_waitcnt lgkmcnt(3)
	v_mfma_f32_16x16x32_bf16 v[102:105], v[182:185], v[166:169], v[102:105]
	v_mfma_f32_16x16x32_bf16 v[46:49], v[182:185], v[170:173], v[46:49]
	v_mfma_f32_16x16x32_bf16 v[30:33], v[182:185], v[174:177], v[30:33]
	v_mfma_f32_16x16x32_bf16 v[14:17], v[182:185], v[178:181], v[14:17]
	s_waitcnt vmcnt(0)
	s_waitcnt lgkmcnt(2)
	v_mfma_f32_16x16x32_bf16 v[82:85], v[206:209], v[166:169], v[82:85]
	ds_write_b128 v194, v[118:121] offset:33792
	v_mfma_f32_16x16x32_bf16 v[42:45], v[206:209], v[170:173], v[42:45]
	ds_write_b128 v194, v[114:117] offset:37888
	v_mfma_f32_16x16x32_bf16 v[26:29], v[206:209], v[174:177], v[26:29]
	ds_write_b128 v193, v[110:113] offset:49152
	v_mfma_f32_16x16x32_bf16 v[10:13], v[206:209], v[178:181], v[10:13]
	ds_write_b128 v193, v[106:109] offset:53248
	s_waitcnt lgkmcnt(5)
	v_mfma_f32_16x16x32_bf16 v[70:73], v[210:213], v[166:169], v[70:73]
	ds_write_b128 v193, v[90:93] offset:57344
	v_mfma_f32_16x16x32_bf16 v[38:41], v[210:213], v[170:173], v[38:41]
	ds_write_b128 v194, v[94:97] offset:28672
	v_mfma_f32_16x16x32_bf16 v[22:25], v[210:213], v[174:177], v[22:25]
	v_mfma_f32_16x16x32_bf16 v[6:9], v[210:213], v[178:181], v[6:9]
	s_waitcnt lgkmcnt(0)
	s_barrier
; #define BLOADG(kt) do { \
;     _Pragma("unroll") for (int i = 0; i < 2; ++i) ra[i] = *(const u32x4*)(ap + (size_t)(64 * i) * lda + (kt) * 32); \
;     _Pragma("unroll") for (int i = 0; i < 4; ++i) rb[i] = *(const u32x4*)(bp + (size_t)((i & 1) * s1 + (i >> 1) * s2) * ldb + (kt) * 32); } while (0)
; #define BSTOREG(st) do { \
;     _Pragma("unroll") for (int i = 0; i < 2; ++i) *(u32x4*)(sA + (st) * BGA + so + 64 * i * 32) = ra[i]; \
;     _Pragma("unroll") for (int i = 0; i < 4; ++i) *(u32x4*)(sB + (st) * BGB + so + 64 * i * 32) = rb[i]; } while (0)
;     ...
;   for (int kt = 0; kt < nk; ++kt) {
;     const int cur = kt & 1;
;     if (kt + 1 < nk) { BSTOREG(cur ^ 1); if (kt + 2 < nk) BLOADG(kt + 2); }
;     const bf16_t* cA = sA + cur * BGA + (wm * 64) * 32 + fo; const bf16_t* cB = sB + cur * BGB + (wn * 128) * 32 + fo;
;     bf16x8 af[4];
; #pragma unroll
;     for (int mi = 0; mi < 4; ++mi) af[mi] = *(const bf16x8*)(cA + mi * 16 * 32);
; #pragma unroll
;     for (int nh = 0; nh < 2; ++nh) {
;       bf16x8 bfr[4];
; #pragma unroll
;       for (int ni = 0; ni < 4; ++ni) bfr[ni] = *(const bf16x8*)(cB + (nh * 4 + ni) * 16 * 32);
; #pragma unroll
;       for (int mi = 0; mi < 4; ++mi)
; #pragma unroll
;         for (int ni = 0; ni < 4; ++ni) acc[mi][nh * 4 + ni] = __builtin_amdgcn_mfma_f32_16x16x32_bf16(bfr[ni], af[mi], acc[mi][nh * 4 + ni], 0, 0, 0);
;     }
;     __syncthreads();
	v_mfma_f32_16x16x32_bf16 v[58:61], v[214:217], v[166:169], v[58:61]
	v_mfma_f32_16x16x32_bf16 v[34:37], v[214:217], v[170:173], v[34:37]
	v_mfma_f32_16x16x32_bf16 v[18:21], v[214:217], v[174:177], v[18:21]
	v_mfma_f32_16x16x32_bf16 v[2:5], v[214:217], v[178:181], v[2:5]
	ds_read_b128 v[166:169], v163 offset:8192
	ds_read_b128 v[170:173], v163 offset:9216
	ds_read_b128 v[174:177], v163 offset:10240
	ds_read_b128 v[178:181], v163 offset:11264
	ds_read_b128 v[182:185], v162 offset:32768
	ds_read_b128 v[206:209], v162 offset:33792
	ds_read_b128 v[210:213], v162 offset:34816
	ds_read_b128 v[214:217], v162 offset:35840
	s_waitcnt lgkmcnt(7)
	s_waitcnt lgkmcnt(3)
	v_mfma_f32_16x16x32_bf16 v[150:153], v[182:185], v[166:169], v[150:153]
	v_mfma_f32_16x16x32_bf16 v[134:137], v[182:185], v[170:173], v[134:137]
	v_mfma_f32_16x16x32_bf16 v[98:101], v[182:185], v[174:177], v[98:101]
	v_mfma_f32_16x16x32_bf16 v[66:69], v[182:185], v[178:181], v[66:69]
	ds_read_b128 v[182:185], v162 offset:36864
	s_sub_u32 m0, m0, 0xb000
	s_nop 0
	global_load_lds_dwordx4 v218, s[26:27]
	global_load_dwordx4 v[118:121], v218, s[26:27] offset:64
	s_waitcnt lgkmcnt(3)
	v_mfma_f32_16x16x32_bf16 v[146:149], v[206:209], v[166:169], v[146:149]
	v_mfma_f32_16x16x32_bf16 v[130:133], v[206:209], v[170:173], v[130:133]
	v_mfma_f32_16x16x32_bf16 v[86:89], v[206:209], v[174:177], v[86:89]
	v_mfma_f32_16x16x32_bf16 v[62:65], v[206:209], v[178:181], v[62:65]
	ds_read_b128 v[206:209], v162 offset:37888
	s_add_u32 m0, m0, 0x1000
	s_nop 0
	global_load_lds_dwordx4 v219, s[26:27]
	global_load_dwordx4 v[114:117], v219, s[26:27] offset:64
	s_waitcnt lgkmcnt(3)
	v_mfma_f32_16x16x32_bf16 v[142:145], v[210:213], v[166:169], v[142:145]
	v_mfma_f32_16x16x32_bf16 v[126:129], v[210:213], v[170:173], v[126:129]
	v_mfma_f32_16x16x32_bf16 v[78:81], v[210:213], v[174:177], v[78:81]
	v_mfma_f32_16x16x32_bf16 v[54:57], v[210:213], v[178:181], v[54:57]
	ds_read_b128 v[210:213], v162 offset:38912
	s_add_u32 m0, m0, 0x3000
	s_nop 0
	global_load_lds_dwordx4 v220, s[28:29]
	global_load_dwordx4 v[110:113], v220, s[28:29] offset:64
	s_waitcnt lgkmcnt(3)
	v_mfma_f32_16x16x32_bf16 v[138:141], v[214:217], v[166:169], v[138:141]
	v_mfma_f32_16x16x32_bf16 v[122:125], v[214:217], v[170:173], v[122:125]
	v_mfma_f32_16x16x32_bf16 v[74:77], v[214:217], v[174:177], v[74:77]
	v_mfma_f32_16x16x32_bf16 v[50:53], v[214:217], v[178:181], v[50:53]
	ds_read_b128 v[214:217], v162 offset:39936
	s_add_u32 m0, m0, 0x1000
	s_nop 0
	global_load_lds_dwordx4 v221, s[28:29]
	global_load_dwordx4 v[106:109], v221, s[28:29] offset:64
	s_waitcnt lgkmcnt(3)
	v_mfma_f32_16x16x32_bf16 v[102:105], v[182:185], v[166:169], v[102:105]
	v_mfma_f32_16x16x32_bf16 v[46:49], v[182:185], v[170:173], v[46:49]
	v_mfma_f32_16x16x32_bf16 v[30:33], v[182:185], v[174:177], v[30:33]
	v_mfma_f32_16x16x32_bf16 v[14:17], v[182:185], v[178:181], v[14:17]
	s_add_u32 m0, m0, 0x1000
	s_nop 0
	global_load_lds_dwordx4 v190, s[28:29]
	global_load_dwordx4 v[90:93], v190, s[28:29] offset:64
	s_waitcnt lgkmcnt(2)
	v_mfma_f32_16x16x32_bf16 v[82:85], v[206:209], v[166:169], v[82:85]
	v_mfma_f32_16x16x32_bf16 v[42:45], v[206:209], v[170:173], v[42:45]
	v_mfma_f32_16x16x32_bf16 v[26:29], v[206:209], v[174:177], v[26:29]
	v_mfma_f32_16x16x32_bf16 v[10:13], v[206:209], v[178:181], v[10:13]
	s_add_u32 m0, m0, 0x1000
	s_nop 0
	global_load_lds_dwordx4 v191, s[28:29]
	global_load_dwordx4 v[94:97], v191, s[28:29] offset:64
	s_add_u32 s26, s26, 0x80
	s_addc_u32 s27, s27, 0
	s_add_u32 s28, s28, 0x80
	s_addc_u32 s29, s29, 0
	s_waitcnt lgkmcnt(1)
	v_mfma_f32_16x16x32_bf16 v[70:73], v[210:213], v[166:169], v[70:73]
	v_mfma_f32_16x16x32_bf16 v[38:41], v[210:213], v[170:173], v[38:41]
	v_mfma_f32_16x16x32_bf16 v[22:25], v[210:213], v[174:177], v[22:25]
	v_mfma_f32_16x16x32_bf16 v[6:9], v[210:213], v[178:181], v[6:9]
	s_waitcnt lgkmcnt(0)
	s_barrier
	v_mfma_f32_16x16x32_bf16 v[58:61], v[214:217], v[166:169], v[58:61]
	v_mfma_f32_16x16x32_bf16 v[34:37], v[214:217], v[170:173], v[34:37]
	v_mfma_f32_16x16x32_bf16 v[18:21], v[214:217], v[174:177], v[18:21]
	v_mfma_f32_16x16x32_bf16 v[2:5], v[214:217], v[178:181], v[2:5]
	ds_read_b128 v[166:169], v192 offset:33792
	ds_read_b128 v[170:173], v192 offset:34816
	ds_read_b128 v[174:177], v192 offset:35840
	ds_read_b128 v[178:181], v192 offset:36864
	ds_read_b128 v[182:185], v162 offset:49152
	ds_read_b128 v[206:209], v162 offset:50176
	ds_read_b128 v[210:213], v162 offset:51200
	ds_read_b128 v[214:217], v162 offset:52224
	s_waitcnt lgkmcnt(7)
	s_waitcnt lgkmcnt(3)
	v_mfma_f32_16x16x32_bf16 v[150:153], v[182:185], v[166:169], v[150:153]
	v_mfma_f32_16x16x32_bf16 v[134:137], v[182:185], v[170:173], v[134:137]
	v_mfma_f32_16x16x32_bf16 v[98:101], v[182:185], v[174:177], v[98:101]
	v_mfma_f32_16x16x32_bf16 v[66:69], v[182:185], v[178:181], v[66:69]
	ds_read_b128 v[182:185], v162 offset:53248
	s_waitcnt lgkmcnt(3)
	v_mfma_f32_16x16x32_bf16 v[146:149], v[206:209], v[166:169], v[146:149]
	v_mfma_f32_16x16x32_bf16 v[130:133], v[206:209], v[170:173], v[130:133]
	v_mfma_f32_16x16x32_bf16 v[86:89], v[206:209], v[174:177], v[86:89]
	v_mfma_f32_16x16x32_bf16 v[62:65], v[206:209], v[178:181], v[62:65]
	ds_read_b128 v[206:209], v162 offset:54272
	s_waitcnt lgkmcnt(3)
	v_mfma_f32_16x16x32_bf16 v[142:145], v[210:213], v[166:169], v[142:145]
	v_mfma_f32_16x16x32_bf16 v[126:129], v[210:213], v[170:173], v[126:129]
	v_mfma_f32_16x16x32_bf16 v[78:81], v[210:213], v[174:177], v[78:81]
	v_mfma_f32_16x16x32_bf16 v[54:57], v[210:213], v[178:181], v[54:57]
	ds_read_b128 v[210:213], v162 offset:55296
	s_waitcnt lgkmcnt(3)
; #define BLOADG(kt) do { \
;     _Pragma("unroll") for (int i = 0; i < 2; ++i) ra[i] = *(const u32x4*)(ap + (size_t)(64 * i) * lda + (kt) * 32); \
;     _Pragma("unroll") for (int i = 0; i < 4; ++i) rb[i] = *(const u32x4*)(bp + (size_t)((i & 1) * s1 + (i >> 1) * s2) * ldb + (kt) * 32); } while (0)
; #define BSTOREG(st) do { \
;     _Pragma("unroll") for (int i = 0; i < 2; ++i) *(u32x4*)(sA + (st) * BGA + so + 64 * i * 32) = ra[i]; \
;     _Pragma("unroll") for (int i = 0; i < 4; ++i) *(u32x4*)(sB + (st) * BGB + so + 64 * i * 32) = rb[i]; } while (0)
;     ...
;   for (int kt = 0; kt < nk; ++kt) {
;     const int cur = kt & 1;
;     if (kt + 1 < nk) { BSTOREG(cur ^ 1); if (kt + 2 < nk) BLOADG(kt + 2); }
;     const bf16_t* cA = sA + cur * BGA + (wm * 64) * 32 + fo; const bf16_t* cB = sB + cur * BGB + (wn * 128) * 32 + fo;
;     bf16x8 af[4];
; #pragma unroll
;     for (int mi = 0; mi < 4; ++mi) af[mi] = *(const bf16x8*)(cA + mi * 16 * 32);
; #pragma unroll
;     for (int nh = 0; nh < 2; ++nh) {
;       bf16x8 bfr[4];
; #pragma unroll
;       for (int ni = 0; ni < 4; ++ni) bfr[ni] = *(const bf16x8*)(cB + (nh * 4 + ni) * 16 * 32);
; #pragma unroll
;       for (int mi = 0; mi < 4; ++mi)
; #pragma unroll
;         for (int ni = 0; ni < 4; ++ni) acc[mi][nh * 4 + ni] = __builtin_amdgcn_mfma_f32_16x16x32_bf16(bfr[ni], af[mi], acc[mi][nh * 4 + ni], 0, 0, 0);
;     }
;     __syncthreads();
	v_mfma_f32_16x16x32_bf16 v[138:141], v[214:217], v[166:169], v[138:141]
	v_mfma_f32_16x16x32_bf16 v[122:125], v[214:217], v[170:173], v[122:125]
	v_mfma_f32_16x16x32_bf16 v[74:77], v[214:217], v[174:177], v[74:77]
	v_mfma_f32_16x16x32_bf16 v[50:53], v[214:217], v[178:181], v[50:53]
	ds_read_b128 v[214:217], v162 offset:56320
	s_waitcnt lgkmcnt(3)
	v_mfma_f32_16x16x32_bf16 v[102:105], v[182:185], v[166:169], v[102:105]
	v_mfma_f32_16x16x32_bf16 v[46:49], v[182:185], v[170:173], v[46:49]
	v_mfma_f32_16x16x32_bf16 v[30:33], v[182:185], v[174:177], v[30:33]
	v_mfma_f32_16x16x32_bf16 v[14:17], v[182:185], v[178:181], v[14:17]
	s_waitcnt vmcnt(0)
	s_waitcnt lgkmcnt(2)
	v_mfma_f32_16x16x32_bf16 v[82:85], v[206:209], v[166:169], v[82:85]
	ds_write_b128 v193, v[118:121] offset:8192
	v_mfma_f32_16x16x32_bf16 v[42:45], v[206:209], v[170:173], v[42:45]
	ds_write_b128 v193, v[114:117] offset:12288
	v_mfma_f32_16x16x32_bf16 v[26:29], v[206:209], v[174:177], v[26:29]
	ds_write_b128 v193, v[110:113] offset:32768
	v_mfma_f32_16x16x32_bf16 v[10:13], v[206:209], v[178:181], v[10:13]
	ds_write_b128 v193, v[106:109] offset:36864
	s_waitcnt lgkmcnt(5)
	v_mfma_f32_16x16x32_bf16 v[70:73], v[210:213], v[166:169], v[70:73]
	ds_write_b128 v193, v[90:93] offset:40960
	v_mfma_f32_16x16x32_bf16 v[38:41], v[210:213], v[170:173], v[38:41]
	ds_write_b128 v193, v[94:97] offset:45056
	v_mfma_f32_16x16x32_bf16 v[22:25], v[210:213], v[174:177], v[22:25]
	v_mfma_f32_16x16x32_bf16 v[6:9], v[210:213], v[178:181], v[6:9]
	s_waitcnt lgkmcnt(0)
	s_barrier
	v_mfma_f32_16x16x32_bf16 v[58:61], v[214:217], v[166:169], v[58:61]
	v_mfma_f32_16x16x32_bf16 v[34:37], v[214:217], v[170:173], v[34:37]
	v_mfma_f32_16x16x32_bf16 v[18:21], v[214:217], v[174:177], v[18:21]
	v_mfma_f32_16x16x32_bf16 v[2:5], v[214:217], v[178:181], v[2:5]
	s_add_i32 s22, s22, 1
	s_cmp_lg_u32 s22, 5
	s_cbranch_scc1 .LBB0_238
	ds_read_b128 v[158:161], v162 offset:16384
	ds_read_b128 v[166:169], v162 offset:17408
	ds_read_b128 v[170:173], v163
	ds_read_b128 v[174:177], v163 offset:1024
	ds_read_b128 v[182:185], v162 offset:18432
	ds_read_b128 v[194:197], v162 offset:19456
	s_lshl_b32 s22, s24, 19
	s_waitcnt lgkmcnt(3)
	v_mfma_f32_16x16x32_bf16 v[178:181], v[158:161], v[170:173], v[150:153]
	v_readlane_b32 s23, v255, 33
	v_readlane_b32 s4, v255, 26
	s_add_i32 s13, s13, s23
	s_waitcnt lgkmcnt(2)
	v_mfma_f32_16x16x32_bf16 v[154:157], v[158:161], v[174:177], v[134:137]
	v_readlane_b32 s23, v255, 30
	s_add_i32 s12, s12, s23
	v_readlane_b32 s23, v255, 34
	s_waitcnt lgkmcnt(1)
	v_mfma_f32_16x16x32_bf16 v[198:201], v[182:185], v[170:173], v[142:145]
	s_add_i32 s11, s11, s23
	v_readlane_b32 s5, v255, 27
	s_waitcnt lgkmcnt(0)
	v_mfma_f32_16x16x32_bf16 v[142:145], v[194:197], v[174:177], v[122:125]
	ds_read_b128 v[210:213], v163 offset:2048
	s_nop 1
	ds_read_b128 v[122:125], v163 offset:3072
	s_waitcnt vmcnt(5)
	ds_write_b128 v193, v[118:121] offset:8192
	s_waitcnt vmcnt(4)
	ds_write_b128 v193, v[114:117] offset:12288
	s_waitcnt vmcnt(3)
	ds_write_b128 v193, v[110:113] offset:32768
	s_waitcnt vmcnt(2)
	ds_write_b128 v193, v[106:109] offset:36864
	v_mfma_f32_16x16x32_bf16 v[206:209], v[194:197], v[170:173], v[138:141]
	v_mfma_f32_16x16x32_bf16 v[150:153], v[166:169], v[174:177], v[130:133]
	s_waitcnt lgkmcnt(5)
	v_mfma_f32_16x16x32_bf16 v[138:141], v[158:161], v[210:213], v[98:101]
	v_mfma_f32_16x16x32_bf16 v[130:133], v[182:185], v[210:213], v[78:81]
	s_waitcnt lgkmcnt(4)
	v_mfma_f32_16x16x32_bf16 v[78:81], v[158:161], v[122:125], v[66:69]
	ds_read_b128 v[158:161], v162 offset:20480
	s_waitcnt vmcnt(1)
	ds_write_b128 v193, v[90:93] offset:40960
	s_waitcnt vmcnt(0)
	ds_write_b128 v193, v[94:97] offset:45056
	ds_read_b128 v[114:117], v162 offset:21504
	v_mfma_f32_16x16x32_bf16 v[190:193], v[166:169], v[170:173], v[146:149]
	v_mfma_f32_16x16x32_bf16 v[146:149], v[182:185], v[174:177], v[126:129]
	v_mfma_f32_16x16x32_bf16 v[126:129], v[194:197], v[210:213], v[74:77]
	v_mfma_f32_16x16x32_bf16 v[74:77], v[166:169], v[122:125], v[62:65]
	v_mfma_f32_16x16x32_bf16 v[62:65], v[194:197], v[122:125], v[50:53]
	ds_read_b128 v[106:109], v162 offset:22528
	s_nop 1
	ds_read_b128 v[50:53], v162 offset:23552
	s_waitcnt lgkmcnt(0)
	s_barrier
	v_mfma_f32_16x16x32_bf16 v[134:137], v[166:169], v[210:213], v[86:89]
	v_mfma_f32_16x16x32_bf16 v[66:69], v[182:185], v[122:125], v[54:57]
	ds_read_b128 v[182:185], v163 offset:8192
	ds_read_b128 v[118:121], v163 offset:9216
	v_mfma_f32_16x16x32_bf16 v[164:167], v[158:161], v[170:173], v[102:105]
	ds_read_b128 v[110:113], v163 offset:10240
	ds_read_b128 v[54:57], v163 offset:11264
	s_nop 0
	ds_read_b128 v[102:105], v162 offset:32768
	ds_read_b128 v[98:101], v162 offset:33792
	v_mfma_f32_16x16x32_bf16 v[194:197], v[114:117], v[170:173], v[82:85]
	ds_read_b128 v[94:97], v162 offset:34816
	ds_read_b128 v[86:89], v162 offset:35840
	ds_read_b128 v[90:93], v162 offset:36864
	ds_read_b128 v[82:85], v162 offset:37888
	v_mfma_f32_16x16x32_bf16 v[214:217], v[106:109], v[170:173], v[70:73]
	v_mfma_f32_16x16x32_bf16 v[168:171], v[50:53], v[170:173], v[58:61]
	s_nop 1
	ds_read_b128 v[70:73], v162 offset:38912
	ds_read_b128 v[58:61], v162 offset:39936
	s_waitcnt lgkmcnt(0)
	s_barrier
; DI int otid() { int t; asm volatile("v_mov_b32 %0, %1" : "=v"(t) : "v"((int)threadIdx.x)); __builtin_assume(t >= 0 && t < 256); return t; }
; DI void outproj_tile(const Params& p, int l, int tile, char* smem) {
;     ...
;   const float* xin = l == 0 ? p.x : p.out;
;   const int lane = otid() & 63, wid = otid() >> 6, wm = wid >> 1, wn = wid & 1, fr = lane & 15, fq = lane >> 4;
; #pragma unroll
;   for (int mi = 0; mi < 4; ++mi)
; #pragma unroll
;     for (int ni = 0; ni < 8; ++ni) {
;       size_t row = (size_t)mt * 128 + wm * 64 + mi * 16 + fr; int col = nt * 256 + wn * 128 + ni * 16 + fq * 4;
;       float4 xi = *(const float4*)(xin + row * 1024 + col);
;       float4 o; o.x = xi.x + acc[mi][ni][0]; o.y = xi.y + acc[mi][ni][1]; o.z = xi.z + acc[mi][ni][2]; o.w = xi.w + acc[mi][ni][3];
;       *(float4*)(p.out + row * 1024 + col) = o;
;     }
	v_mov_b32 v0, v188
	v_mov_b32 v162, v188
	v_mfma_f32_16x16x32_bf16 v[46:49], v[158:161], v[174:177], v[46:49]
	v_and_b32_e32 v163, 15, v0
	v_lshrrev_b32_e32 v172, 1, v162
	v_lshlrev_b32_e32 v162, 1, v162
	v_lshrrev_b32_e32 v0, 2, v0
	v_and_b32_e32 v162, 0x80, v162
	v_and_b32_e32 v0, 12, v0
	v_mfma_f32_16x16x32_bf16 v[42:45], v[114:117], v[174:177], v[42:45]
	v_and_or_b32 v163, v172, 64, v163
	v_mfma_f32_16x16x32_bf16 v[38:41], v[106:109], v[174:177], v[38:41]
	v_mfma_f32_16x16x32_bf16 v[172:175], v[50:53], v[174:177], v[34:37]
	s_nop 2
	v_or3_b32 v34, v0, v162, s25
	v_ashrrev_i32_e32 v35, 31, v34
	v_lshl_or_b32 v0, v163, 12, s22
	v_lshl_add_u64 v[36:37], s[0:1], 0, v[0:1]
	v_lshlrev_b64 v[34:35], 2, v[34:35]
	v_lshl_add_u64 v[36:37], v[36:37], 0, v[34:35]
	global_load_dwordx4 v[218:221], v[36:37], off
	v_mfma_f32_16x16x32_bf16 v[176:179], v[102:105], v[182:185], v[178:181]
	v_lshl_add_u64 v[162:163], s[56:57], 0, v[0:1]
	v_lshl_add_u64 v[186:187], v[162:163], 0, v[34:35]
	s_lshr_b32 s22, s4, 3
	v_mfma_f32_16x16x32_bf16 v[190:193], v[98:101], v[182:185], v[190:193]
	s_add_i32 s7, s7, s22
	s_cmpk_gt_i32 s13, 0x7f
	s_waitcnt vmcnt(0)
	s_nop 0
	v_add_f32_e32 v176, v176, v218
	v_add_f32_e32 v177, v177, v219
	v_add_f32_e32 v178, v178, v220
	v_add_f32_e32 v179, v179, v221
	global_store_dwordx4 v[186:187], v[176:179], off
	global_load_dwordx4 v[176:179], v[36:37], off offset:64
	v_mfma_f32_16x16x32_bf16 v[162:165], v[90:93], v[182:185], v[164:167]
	s_waitcnt vmcnt(0)
	v_add_f32_e32 v176, v190, v176
	v_add_f32_e32 v177, v191, v177
	v_add_f32_e32 v178, v192, v178
	v_add_f32_e32 v179, v193, v179
	global_store_dwordx4 v[186:187], v[176:179], off offset:64
	global_load_dwordx4 v[176:179], v[36:37], off offset:128
	v_mfma_f32_16x16x32_bf16 v[190:193], v[94:97], v[182:185], v[198:201]
	v_mfma_f32_16x16x32_bf16 v[30:33], v[158:161], v[210:213], v[30:33]
	v_mfma_f32_16x16x32_bf16 v[14:17], v[158:161], v[122:125], v[14:17]
	s_waitcnt vmcnt(0)
	s_nop 4
	v_add_f32_e32 v176, v190, v176
	v_add_f32_e32 v177, v191, v177
	v_add_f32_e32 v178, v192, v178
	v_add_f32_e32 v179, v193, v179
	global_store_dwordx4 v[186:187], v[176:179], off offset:128
	global_load_dwordx4 v[176:179], v[36:37], off offset:192
	v_mfma_f32_16x16x32_bf16 v[190:193], v[86:89], v[182:185], v[206:209]
	v_mfma_f32_16x16x32_bf16 v[154:157], v[102:105], v[118:121], v[154:157]
	v_mfma_f32_16x16x32_bf16 v[150:153], v[98:101], v[118:121], v[150:153]
	s_waitcnt vmcnt(0)
	s_nop 4
	v_add_f32_e32 v176, v190, v176
	v_add_f32_e32 v177, v191, v177
	v_add_f32_e32 v178, v192, v178
	v_add_f32_e32 v179, v193, v179
	global_store_dwordx4 v[186:187], v[176:179], off offset:192
	global_load_dwordx4 v[176:179], v[36:37], off offset:256
	v_mfma_f32_16x16x32_bf16 v[146:149], v[94:97], v[118:121], v[146:149]
	s_waitcnt vmcnt(0)
	v_add_f32_e32 v162, v162, v176
	v_add_f32_e32 v163, v163, v177
	v_add_f32_e32 v164, v164, v178
	v_add_f32_e32 v165, v165, v179
	global_store_dwordx4 v[186:187], v[162:165], off offset:256
	global_load_dwordx4 v[162:165], v[36:37], off offset:320
	v_mfma_f32_16x16x32_bf16 v[176:179], v[82:85], v[182:185], v[194:197]
	v_mfma_f32_16x16x32_bf16 v[142:145], v[86:89], v[118:121], v[142:145]
	v_mfma_f32_16x16x32_bf16 v[46:49], v[90:93], v[118:121], v[46:49]
	s_waitcnt vmcnt(0)
	s_nop 4
	v_add_f32_e32 v162, v176, v162
	v_add_f32_e32 v163, v177, v163
	v_add_f32_e32 v164, v178, v164
	v_add_f32_e32 v165, v179, v165
	global_store_dwordx4 v[186:187], v[162:165], off offset:320
	global_load_dwordx4 v[162:165], v[36:37], off offset:384
	v_mfma_f32_16x16x32_bf16 v[176:179], v[70:73], v[182:185], v[214:217]
	v_mfma_f32_16x16x32_bf16 v[42:45], v[82:85], v[118:121], v[42:45]
	v_mfma_f32_16x16x32_bf16 v[30:33], v[90:93], v[110:113], v[30:33]
	s_waitcnt vmcnt(0)
	s_nop 4
	v_add_f32_e32 v162, v176, v162
	v_add_f32_e32 v163, v177, v163
	v_add_f32_e32 v164, v178, v164
	v_add_f32_e32 v165, v179, v165
	global_store_dwordx4 v[186:187], v[162:165], off offset:384
	global_load_dwordx4 v[162:165], v[36:37], off offset:448
	v_mov_b32_e32 v37, v1
	v_or_b32_e32 v36, 0x10000, v0
	v_lshl_add_u64 v[158:159], s[0:1], 0, v[36:37]
	v_lshl_add_u64 v[166:167], v[158:159], 0, v[34:35]
	v_mfma_f32_16x16x32_bf16 v[158:161], v[58:61], v[182:185], v[168:171]
	v_lshl_add_u64 v[36:37], s[56:57], 0, v[36:37]
	v_mfma_f32_16x16x32_bf16 v[26:29], v[114:117], v[210:213], v[26:29]
	v_mfma_f32_16x16x32_bf16 v[26:29], v[82:85], v[110:113], v[26:29]
	s_waitcnt vmcnt(0)
	s_nop 3
	v_add_f32_e32 v158, v158, v162
	v_add_f32_e32 v159, v159, v163
	v_add_f32_e32 v160, v160, v164
	v_add_f32_e32 v161, v161, v165
	global_store_dwordx4 v[186:187], v[158:161], off offset:448
	global_load_dwordx4 v[158:161], v[166:167], off
	v_lshl_add_u64 v[162:163], v[36:37], 0, v[34:35]
	v_mfma_f32_16x16x32_bf16 v[36:39], v[70:73], v[118:121], v[38:41]
	s_waitcnt vmcnt(0)
	v_add_f32_e32 v154, v154, v158
	v_add_f32_e32 v155, v155, v159
	v_add_f32_e32 v156, v156, v160
	v_add_f32_e32 v157, v157, v161
	global_store_dwordx4 v[162:163], v[154:157], off
	global_load_dwordx4 v[154:157], v[166:167], off offset:64
	v_mfma_f32_16x16x32_bf16 v[22:25], v[106:109], v[210:213], v[22:25]
	s_waitcnt vmcnt(0)
	v_add_f32_e32 v150, v150, v154
	v_add_f32_e32 v151, v151, v155
	v_add_f32_e32 v152, v152, v156
	v_add_f32_e32 v153, v153, v157
	global_store_dwordx4 v[162:163], v[150:153], off offset:64
	global_load_dwordx4 v[150:153], v[166:167], off offset:128
	v_mfma_f32_16x16x32_bf16 v[22:25], v[70:73], v[110:113], v[22:25]
	s_waitcnt vmcnt(0)
; DI int otid() { int t; asm volatile("v_mov_b32 %0, %1" : "=v"(t) : "v"((int)threadIdx.x)); __builtin_assume(t >= 0 && t < 256); return t; }
; DI void outproj_tile(const Params& p, int l, int tile, char* smem) {
;     ...
;   const float* xin = l == 0 ? p.x : p.out;
;   const int lane = otid() & 63, wid = otid() >> 6, wm = wid >> 1, wn = wid & 1, fr = lane & 15, fq = lane >> 4;
; #pragma unroll
;   for (int mi = 0; mi < 4; ++mi)
; #pragma unroll
;     for (int ni = 0; ni < 8; ++ni) {
;       size_t row = (size_t)mt * 128 + wm * 64 + mi * 16 + fr; int col = nt * 256 + wn * 128 + ni * 16 + fq * 4;
;       float4 xi = *(const float4*)(xin + row * 1024 + col);
;       float4 o; o.x = xi.x + acc[mi][ni][0]; o.y = xi.y + acc[mi][ni][1]; o.z = xi.z + acc[mi][ni][2]; o.w = xi.w + acc[mi][ni][3];
;       *(float4*)(p.out + row * 1024 + col) = o;
;     }
	v_add_f32_e32 v146, v146, v150
	v_add_f32_e32 v147, v147, v151
	v_add_f32_e32 v148, v148, v152
	v_add_f32_e32 v149, v149, v153
	global_store_dwordx4 v[162:163], v[146:149], off offset:128
	global_load_dwordx4 v[146:149], v[166:167], off offset:192
	v_mfma_f32_16x16x32_bf16 v[18:21], v[50:53], v[210:213], v[18:21]
	s_waitcnt vmcnt(0)
	v_add_f32_e32 v142, v142, v146
	v_add_f32_e32 v143, v143, v147
	v_add_f32_e32 v144, v144, v148
	v_add_f32_e32 v145, v145, v149
	global_store_dwordx4 v[162:163], v[142:145], off offset:192
	global_load_dwordx4 v[142:145], v[166:167], off offset:256
	v_mfma_f32_16x16x32_bf16 v[18:21], v[58:61], v[110:113], v[18:21]
	s_waitcnt vmcnt(0)
	v_add_f32_e32 v46, v46, v142
	v_add_f32_e32 v47, v47, v143
	v_add_f32_e32 v48, v48, v144
	v_add_f32_e32 v49, v49, v145
	global_store_dwordx4 v[162:163], v[46:49], off offset:256
	global_load_dwordx4 v[46:49], v[166:167], off offset:320
	v_mfma_f32_16x16x32_bf16 v[14:17], v[90:93], v[54:57], v[14:17]
	s_waitcnt vmcnt(0)
	v_add_f32_e32 v42, v42, v46
	v_add_f32_e32 v43, v43, v47
	v_add_f32_e32 v44, v44, v48
	v_add_f32_e32 v45, v45, v49
	global_store_dwordx4 v[162:163], v[42:45], off offset:320
	global_load_dwordx4 v[42:45], v[166:167], off offset:384
	v_mfma_f32_16x16x32_bf16 v[10:13], v[114:117], v[122:125], v[10:13]
	s_waitcnt vmcnt(0)
	v_add_f32_e32 v36, v36, v42
	v_add_f32_e32 v37, v37, v43
	v_add_f32_e32 v38, v38, v44
	v_add_f32_e32 v39, v39, v45
	global_store_dwordx4 v[162:163], v[36:39], off offset:384
	global_load_dwordx4 v[36:39], v[166:167], off offset:448
	v_mov_b32_e32 v45, v1
	v_or_b32_e32 v44, 0x20000, v0
	v_lshl_add_u64 v[40:41], s[0:1], 0, v[44:45]
	v_lshl_add_u64 v[46:47], v[40:41], 0, v[34:35]
	v_mfma_f32_16x16x32_bf16 v[40:43], v[58:61], v[118:121], v[172:175]
	v_or_b32_e32 v0, 0x30000, v0
	v_mfma_f32_16x16x32_bf16 v[10:13], v[82:85], v[54:57], v[10:13]
	v_mfma_f32_16x16x32_bf16 v[6:9], v[106:109], v[122:125], v[6:9]
	s_waitcnt vmcnt(0)
	s_nop 3
	v_add_f32_e32 v36, v40, v36
	v_add_f32_e32 v37, v41, v37
	v_add_f32_e32 v38, v42, v38
	v_add_f32_e32 v39, v43, v39
	global_store_dwordx4 v[162:163], v[36:39], off offset:448
	global_load_dwordx4 v[36:39], v[46:47], off
	v_lshl_add_u64 v[40:41], s[56:57], 0, v[44:45]
	v_lshl_add_u64 v[44:45], v[40:41], 0, v[34:35]
	v_mfma_f32_16x16x32_bf16 v[40:43], v[102:105], v[110:113], v[138:141]
	v_mfma_f32_16x16x32_bf16 v[6:9], v[70:73], v[54:57], v[6:9]
	v_mfma_f32_16x16x32_bf16 v[2:5], v[50:53], v[122:125], v[2:5]
	s_waitcnt vmcnt(0)
	s_nop 4
	v_add_f32_e32 v36, v40, v36
	v_add_f32_e32 v37, v41, v37
	v_add_f32_e32 v38, v42, v38
	v_add_f32_e32 v39, v43, v39
	global_store_dwordx4 v[44:45], v[36:39], off
	global_load_dwordx4 v[36:39], v[46:47], off offset:64
	v_mfma_f32_16x16x32_bf16 v[40:43], v[98:101], v[110:113], v[134:137]
	v_mfma_f32_16x16x32_bf16 v[2:5], v[58:61], v[54:57], v[2:5]
	s_waitcnt vmcnt(0)
	s_nop 5
	v_add_f32_e32 v36, v40, v36
	v_add_f32_e32 v37, v41, v37
	v_add_f32_e32 v38, v42, v38
	v_add_f32_e32 v39, v43, v39
	global_store_dwordx4 v[44:45], v[36:39], off offset:64
	global_load_dwordx4 v[36:39], v[46:47], off offset:128
	v_mfma_f32_16x16x32_bf16 v[40:43], v[94:97], v[110:113], v[130:133]
	s_waitcnt vmcnt(0)
	s_nop 6
	v_add_f32_e32 v36, v40, v36
	v_add_f32_e32 v37, v41, v37
	v_add_f32_e32 v38, v42, v38
	v_add_f32_e32 v39, v43, v39
	global_store_dwordx4 v[44:45], v[36:39], off offset:128
	global_load_dwordx4 v[36:39], v[46:47], off offset:192
	v_mfma_f32_16x16x32_bf16 v[40:43], v[86:89], v[110:113], v[126:129]
	s_waitcnt vmcnt(0)
; DI int otid() { int t; asm volatile("v_mov_b32 %0, %1" : "=v"(t) : "v"((int)threadIdx.x)); __builtin_assume(t >= 0 && t < 256); return t; }
; DI void outproj_tile(const Params& p, int l, int tile, char* smem) {
;     ...
;   const float* xin = l == 0 ? p.x : p.out;
;   const int lane = otid() & 63, wid = otid() >> 6, wm = wid >> 1, wn = wid & 1, fr = lane & 15, fq = lane >> 4;
; #pragma unroll
;   for (int mi = 0; mi < 4; ++mi)
; #pragma unroll
;     for (int ni = 0; ni < 8; ++ni) {
;       size_t row = (size_t)mt * 128 + wm * 64 + mi * 16 + fr; int col = nt * 256 + wn * 128 + ni * 16 + fq * 4;
;       float4 xi = *(const float4*)(xin + row * 1024 + col);
;       float4 o; o.x = xi.x + acc[mi][ni][0]; o.y = xi.y + acc[mi][ni][1]; o.z = xi.z + acc[mi][ni][2]; o.w = xi.w + acc[mi][ni][3];
;       *(float4*)(p.out + row * 1024 + col) = o;
;     }
	s_nop 6
	v_add_f32_e32 v36, v40, v36
	v_add_f32_e32 v37, v41, v37
	v_add_f32_e32 v38, v42, v38
	v_add_f32_e32 v39, v43, v39
	global_store_dwordx4 v[44:45], v[36:39], off offset:192
	global_load_dwordx4 v[36:39], v[46:47], off offset:256
	s_waitcnt vmcnt(0)
	v_add_f32_e32 v30, v30, v36
	v_add_f32_e32 v31, v31, v37
	v_add_f32_e32 v32, v32, v38
	v_add_f32_e32 v33, v33, v39
	global_store_dwordx4 v[44:45], v[30:33], off offset:256
	global_load_dwordx4 v[30:33], v[46:47], off offset:320
	s_waitcnt vmcnt(0)
	v_add_f32_e32 v26, v26, v30
	v_add_f32_e32 v27, v27, v31
	v_add_f32_e32 v28, v28, v32
	v_add_f32_e32 v29, v29, v33
	global_store_dwordx4 v[44:45], v[26:29], off offset:320
	global_load_dwordx4 v[26:29], v[46:47], off offset:384
	s_waitcnt vmcnt(0)
	v_add_f32_e32 v22, v22, v26
	v_add_f32_e32 v23, v23, v27
	v_add_f32_e32 v24, v24, v28
	v_add_f32_e32 v25, v25, v29
	global_store_dwordx4 v[44:45], v[22:25], off offset:384
	global_load_dwordx4 v[22:25], v[46:47], off offset:448
	v_lshl_add_u64 v[26:27], s[0:1], 0, v[0:1]
	v_lshl_add_u64 v[26:27], v[26:27], 0, v[34:35]
	s_waitcnt vmcnt(0)
	v_add_f32_e32 v18, v18, v22
	v_add_f32_e32 v19, v19, v23
	v_add_f32_e32 v20, v20, v24
	v_add_f32_e32 v21, v21, v25
	global_store_dwordx4 v[44:45], v[18:21], off offset:448
	global_load_dwordx4 v[18:21], v[26:27], off
	v_lshl_add_u64 v[22:23], s[56:57], 0, v[0:1]
	v_lshl_add_u64 v[28:29], v[22:23], 0, v[34:35]
	v_mfma_f32_16x16x32_bf16 v[22:25], v[102:105], v[54:57], v[78:81]
	s_waitcnt vmcnt(0)
	s_nop 6
	v_add_f32_e32 v18, v22, v18
	v_add_f32_e32 v19, v23, v19
	v_add_f32_e32 v20, v24, v20
	v_add_f32_e32 v21, v25, v21
	global_store_dwordx4 v[28:29], v[18:21], off
	global_load_dwordx4 v[18:21], v[26:27], off offset:64
	v_mfma_f32_16x16x32_bf16 v[22:25], v[98:101], v[54:57], v[74:77]
	s_waitcnt vmcnt(0)
	s_nop 6
	v_add_f32_e32 v18, v22, v18
	v_add_f32_e32 v19, v23, v19
	v_add_f32_e32 v20, v24, v20
	v_add_f32_e32 v21, v25, v21
	global_store_dwordx4 v[28:29], v[18:21], off offset:64
	global_load_dwordx4 v[18:21], v[26:27], off offset:128
	v_mfma_f32_16x16x32_bf16 v[22:25], v[94:97], v[54:57], v[66:69]
	s_waitcnt vmcnt(0)
	s_nop 6
	v_add_f32_e32 v18, v22, v18
	v_add_f32_e32 v19, v23, v19
	v_add_f32_e32 v20, v24, v20
	v_add_f32_e32 v21, v25, v21
	global_store_dwordx4 v[28:29], v[18:21], off offset:128
	global_load_dwordx4 v[18:21], v[26:27], off offset:192
	v_mfma_f32_16x16x32_bf16 v[22:25], v[86:89], v[54:57], v[62:65]
	s_waitcnt vmcnt(0)
	s_nop 6
	v_add_f32_e32 v18, v22, v18
	v_add_f32_e32 v19, v23, v19
	v_add_f32_e32 v20, v24, v20
	v_add_f32_e32 v21, v25, v21
	global_store_dwordx4 v[28:29], v[18:21], off offset:192
	global_load_dwordx4 v[18:21], v[26:27], off offset:256
	s_waitcnt vmcnt(0)
	v_add_f32_e32 v14, v14, v18
	v_add_f32_e32 v15, v15, v19
	v_add_f32_e32 v16, v16, v20
	v_add_f32_e32 v17, v17, v21
	global_store_dwordx4 v[28:29], v[14:17], off offset:256
	global_load_dwordx4 v[14:17], v[26:27], off offset:320
	s_waitcnt vmcnt(0)
	v_add_f32_e32 v10, v10, v14
	v_add_f32_e32 v11, v11, v15
	v_add_f32_e32 v12, v12, v16
	v_add_f32_e32 v13, v13, v17
	global_store_dwordx4 v[28:29], v[10:13], off offset:320
	global_load_dwordx4 v[10:13], v[26:27], off offset:384
	s_waitcnt vmcnt(0)
	v_add_f32_e32 v6, v6, v10
	v_add_f32_e32 v7, v7, v11
	v_add_f32_e32 v8, v8, v12
	v_add_f32_e32 v9, v9, v13
	global_store_dwordx4 v[28:29], v[6:9], off offset:384
	global_load_dwordx4 v[6:9], v[26:27], off offset:448
	s_waitcnt vmcnt(0)
	v_add_f32_e32 v2, v2, v6
	v_add_f32_e32 v3, v3, v7
	v_add_f32_e32 v4, v4, v8
	v_add_f32_e32 v5, v5, v9
	global_store_dwordx4 v[28:29], v[2:5], off offset:448
	s_cbranch_scc0 .LBB0_237
